# attention unit output: half-wave exchange (v_permlane32_swap) + 4 dwordx4 stores instead of 8 dwordx2
# speedup vs baseline: 1.0033x; 1.0033x over previous
; DI unsigned pack2(float a, float b) { f2_t f = {a, b}; bf2_t r = __builtin_convertvector(f, bf2_t); return __builtin_bit_cast(unsigned, r); }
; template <int DQK, bool NA>
; DI void attn_unit(const bf16_t* __restrict__ Qb, int ldq, const bf16_t* __restrict__ Kb, int ldk, const bf16_t* __restrict__ Vt,
;                   bf16_t* __restrict__ Ob, int ldo, int u, float sc, const float* __restrict__ rpb_h, char* smem) {
;     ...
;   l_run += __shfl_xor(l_run, 32);
;   const float inv = 1.f / l_run;
;   bf16_t* op = Ob + (size_t)(256 * u + 32 * w + r) * ldo;
; #pragma unroll
;   for (int g = 0; g < 4; ++g) {
;     u32x2 a = {pack2(o0[4 * g] * inv, o0[4 * g + 1] * inv), pack2(o0[4 * g + 2] * inv, o0[4 * g + 3] * inv)};
;     u32x2 b = {pack2(o1[4 * g] * inv, o1[4 * g + 1] * inv), pack2(o1[4 * g + 2] * inv, o1[4 * g + 3] * inv)};
;     *(u32x2*)(op + 8 * g + 4 * h) = a;
;     *(u32x2*)(op + 32 + 8 * g + 4 * h) = b;
;   }
.LBB0_390:
	v_div_scale_f32 v4, s[2:3], v0, v0, 1.0
	v_rcp_f32_e32 v5, v4
	v_div_scale_f32 v6, vcc, 1.0, v0, 1.0
	v_mov_b32_e32 v115, v1
	v_fma_f32 v7, -v4, v5, 1.0
	v_fmac_f32_e32 v5, v7, v5
	v_mul_f32_e32 v7, v6, v5
	v_fma_f32 v8, -v4, v7, v6
	v_fmac_f32_e32 v7, v8, v5
	v_fma_f32 v4, -v4, v7, v6
	v_div_fmas_f32 v4, v4, v5, v7
	v_div_fixup_f32 v0, v4, v0, 1.0
	v_lshl_add_u64 v[2:3], v[114:115], 1, v[2:3]
	v_and_b32_e32 v10, 32, v197
	v_lshrrev_b32_e32 v10, 2, v10
	v_mov_b32_e32 v11, 0
	v_lshl_add_u64 v[2:3], v[2:3], 0, v[10:11]
	v_pk_mul_f32 v[4:5], v[32:33], v[0:1] op_sel_hi:[1,0]
	v_pk_mul_f32 v[6:7], v[34:35], v[0:1] op_sel_hi:[1,0]
	v_cvt_pk_bf16_f32 v64, v4, v5
	v_cvt_pk_bf16_f32 v65, v6, v7
	v_pk_mul_f32 v[4:5], v[36:37], v[0:1] op_sel_hi:[1,0]
	v_pk_mul_f32 v[6:7], v[38:39], v[0:1] op_sel_hi:[1,0]
	v_cvt_pk_bf16_f32 v66, v4, v5
	v_cvt_pk_bf16_f32 v67, v6, v7
	v_pk_mul_f32 v[4:5], v[40:41], v[0:1] op_sel_hi:[1,0]
	v_pk_mul_f32 v[6:7], v[42:43], v[0:1] op_sel_hi:[1,0]
	v_cvt_pk_bf16_f32 v68, v4, v5
	v_cvt_pk_bf16_f32 v69, v6, v7
	v_pk_mul_f32 v[4:5], v[44:45], v[0:1] op_sel_hi:[1,0]
	v_pk_mul_f32 v[6:7], v[46:47], v[0:1] op_sel_hi:[1,0]
	v_cvt_pk_bf16_f32 v70, v4, v5
	v_cvt_pk_bf16_f32 v71, v6, v7
	v_pk_mul_f32 v[6:7], v[0:1], v[16:17] op_sel_hi:[0,1]
	v_pk_mul_f32 v[8:9], v[0:1], v[18:19] op_sel_hi:[0,1]
	v_cvt_pk_bf16_f32 v72, v6, v7
	v_cvt_pk_bf16_f32 v73, v8, v9
	v_pk_mul_f32 v[6:7], v[0:1], v[20:21] op_sel_hi:[0,1]
	v_pk_mul_f32 v[8:9], v[0:1], v[22:23] op_sel_hi:[0,1]
	v_cvt_pk_bf16_f32 v74, v6, v7
	v_cvt_pk_bf16_f32 v75, v8, v9
	v_pk_mul_f32 v[6:7], v[0:1], v[24:25] op_sel_hi:[0,1]
	v_pk_mul_f32 v[8:9], v[0:1], v[26:27] op_sel_hi:[0,1]
	v_cvt_pk_bf16_f32 v76, v6, v7
	v_cvt_pk_bf16_f32 v77, v8, v9
	v_pk_mul_f32 v[6:7], v[0:1], v[28:29] op_sel_hi:[0,1]
	v_pk_mul_f32 v[8:9], v[0:1], v[30:31] op_sel_hi:[0,1]
	v_cvt_pk_bf16_f32 v78, v6, v7
	v_cvt_pk_bf16_f32 v79, v8, v9
	s_mov_b32 s1, 0
	s_nop 1
	v_permlane32_swap_b32_e32 v64, v66
	v_permlane32_swap_b32_e32 v65, v67
	v_permlane32_swap_b32_e32 v68, v70
	v_permlane32_swap_b32_e32 v69, v71
	v_permlane32_swap_b32_e32 v72, v74
	v_permlane32_swap_b32_e32 v73, v75
	v_permlane32_swap_b32_e32 v76, v78
	v_permlane32_swap_b32_e32 v77, v79
	s_nop 0
	global_store_dwordx4 v[2:3], v[64:67], off
	global_store_dwordx4 v[2:3], v[68:71], off offset:32
	global_store_dwordx4 v[2:3], v[72:75], off offset:64
	global_store_dwordx4 v[2:3], v[76:79], off offset:96
